# SGPR-base LDS-DMA attention loop with the loop head re-phased to an 8-byte boundary (one pad nop before the loop)
# baseline (speedup 1.0000x reference)
; __device__ __forceinline__ void attn_unit(const Ctx& C, const bf16* Zqkv, const bf16* Kp, const bf16* Vp, const bf16* Zbg, bf16* Bp, const float* sg, float lam, float omli, int h, int qrow0, int seqlen, const unsigned* knmax) {
;     ...
;     int s0 = 0, s1 = 1, s2 = 2;
;     f32x16 o[4];
; #pragma unroll
;     for (int db = 0; db < 4; ++db) o[db] = f32x16{};
;     const f32x16 zero16 = f32x16{};
;     float mhat = 0.f, lsum = 0.f; bool shifted = false;
.LBB0_419:
	v_mov_b32_e32 v14, v1
	v_mov_b32_e32 v15, v1
	v_mov_b32_e32 v0, v1
	v_mov_b32_e32 v2, v1
	v_mov_b32_e32 v3, v1
	v_mov_b32_e32 v4, v1
	v_mov_b32_e32 v5, v1
	v_mov_b32_e32 v6, v1
	v_mov_b32_e32 v7, v1
	v_mov_b32_e32 v8, v1
	v_mov_b32_e32 v9, v1
	v_mov_b32_e32 v10, v1
	v_mov_b32_e32 v11, v1
	v_mov_b32_e32 v12, v1
	v_mov_b32_e32 v13, v1
	s_cmp_lg_u64 s[6:7], 0
	v_mov_b64_e32 v[30:31], v[14:15]
	v_mov_b64_e32 v[46:47], v[14:15]
	v_mov_b64_e32 v[62:63], v[14:15]
	v_mov_b64_e32 v[78:79], v[14:15]
	s_mov_b32 s54, 0
	v_mov_b32_e32 v236, 0
	s_mov_b32 s47, 2
	s_mov_b32 s46, 1
	s_mov_b32 s45, 4
	s_cselect_b64 s[0:1], -1, 0
	v_mov_b64_e32 v[28:29], v[12:13]
	v_mov_b64_e32 v[26:27], v[10:11]
	v_mov_b64_e32 v[24:25], v[8:9]
	v_mov_b64_e32 v[22:23], v[6:7]
	v_mov_b64_e32 v[20:21], v[4:5]
	v_mov_b64_e32 v[18:19], v[2:3]
	v_mov_b64_e32 v[16:17], v[0:1]
	v_mov_b64_e32 v[44:45], v[12:13]
	v_mov_b64_e32 v[42:43], v[10:11]
	v_mov_b64_e32 v[40:41], v[8:9]
	v_mov_b64_e32 v[38:39], v[6:7]
	v_mov_b64_e32 v[36:37], v[4:5]
	v_mov_b64_e32 v[34:35], v[2:3]
	v_mov_b64_e32 v[32:33], v[0:1]
	v_mov_b64_e32 v[60:61], v[12:13]
	v_mov_b64_e32 v[58:59], v[10:11]
	v_mov_b64_e32 v[56:57], v[8:9]
	v_mov_b64_e32 v[54:55], v[6:7]
	v_mov_b64_e32 v[52:53], v[4:5]
	v_mov_b64_e32 v[50:51], v[2:3]
	v_mov_b64_e32 v[48:49], v[0:1]
	v_mov_b64_e32 v[76:77], v[12:13]
	v_mov_b64_e32 v[74:75], v[10:11]
	v_mov_b64_e32 v[72:73], v[8:9]
	v_mov_b64_e32 v[70:71], v[6:7]
	v_mov_b64_e32 v[68:69], v[4:5]
	v_mov_b64_e32 v[66:67], v[2:3]
	v_mov_b64_e32 v[64:65], v[0:1]
	s_mov_b32 s49, m0
	v_readfirstlane_b32 s98, v188
	v_readfirstlane_b32 s99, v189
	v_readfirstlane_b32 s100, v190
	v_readfirstlane_b32 s101, v191
	v_lshlrev_b32_e32 v237, 4, v201
	s_nop 3
	s_nop 0
	s_mov_b32 s45, 0
	s_mov_b32 s46, 0
	s_mov_b32 s47, 1
	s_mov_b32 s54, 2
	v_exp_f32_e32 v96, v96
	v_exp_f32_e32 v97, v97
	v_exp_f32_e32 v98, v98
	v_exp_f32_e32 v99, v99
	v_exp_f32_e32 v100, v100
	v_exp_f32_e32 v101, v101
	v_exp_f32_e32 v102, v102
	v_exp_f32_e32 v103, v103
	v_add_f32_e32 v0, v96, v97
	v_add_f32_e32 v14, v98, v99
	v_add_f32_e32 v15, v0, v14
	v_cvt_pk_bf16_f32 v112, v96, v97
	v_cvt_pk_bf16_f32 v113, v98, v99
	v_exp_f32_e32 v104, v104
	v_exp_f32_e32 v105, v105
	v_exp_f32_e32 v106, v106
	v_exp_f32_e32 v107, v107
	v_add_f32_e32 v0, v100, v101
	v_add_f32_e32 v14, v102, v103
	v_add_f32_e32 v0, v0, v14
	v_add_f32_e32 v15, v15, v0
	v_cvt_pk_bf16_f32 v114, v100, v101
	v_cvt_pk_bf16_f32 v115, v102, v103
	v_exp_f32_e32 v108, v108
	v_exp_f32_e32 v109, v109
	v_exp_f32_e32 v110, v110
	v_exp_f32_e32 v111, v111
	v_add_f32_e32 v0, v104, v105
	v_add_f32_e32 v14, v106, v107
	v_add_f32_e32 v0, v0, v14
	v_add_f32_e32 v15, v15, v0
	v_cvt_pk_bf16_f32 v116, v104, v105
	v_cvt_pk_bf16_f32 v117, v106, v107
	v_exp_f32_e32 v80, v80
	v_exp_f32_e32 v81, v81
	v_exp_f32_e32 v82, v82
	v_exp_f32_e32 v83, v83
	v_add_f32_e32 v0, v108, v109
	v_add_f32_e32 v14, v110, v111
	v_add_f32_e32 v0, v0, v14
	v_add_f32_e32 v15, v15, v0
	v_cvt_pk_bf16_f32 v118, v108, v109
	v_cvt_pk_bf16_f32 v119, v110, v111
	v_exp_f32_e32 v84, v84
	v_exp_f32_e32 v85, v85
	v_exp_f32_e32 v86, v86
	v_exp_f32_e32 v87, v87
	v_add_f32_e32 v0, v80, v81
	v_add_f32_e32 v14, v82, v83
	v_add_f32_e32 v0, v0, v14
	v_add_f32_e32 v15, v15, v0
	v_cvt_pk_bf16_f32 v120, v80, v81
	v_cvt_pk_bf16_f32 v121, v82, v83
	v_exp_f32_e32 v88, v88
	v_exp_f32_e32 v89, v89
	v_exp_f32_e32 v90, v90
	v_exp_f32_e32 v91, v91
	v_add_f32_e32 v0, v84, v85
	v_add_f32_e32 v14, v86, v87
	v_add_f32_e32 v0, v0, v14
	v_add_f32_e32 v15, v15, v0
	v_cvt_pk_bf16_f32 v122, v84, v85
	v_cvt_pk_bf16_f32 v123, v86, v87
	v_exp_f32_e32 v92, v92
	v_exp_f32_e32 v93, v93
	v_exp_f32_e32 v94, v94
	v_exp_f32_e32 v95, v95
	v_add_f32_e32 v0, v88, v89
	v_add_f32_e32 v14, v90, v91
	v_add_f32_e32 v0, v0, v14
	v_add_f32_e32 v15, v15, v0
	v_cvt_pk_bf16_f32 v124, v88, v89
	v_cvt_pk_bf16_f32 v125, v90, v91
	v_add_f32_e32 v0, v92, v93
	v_add_f32_e32 v14, v94, v95
	v_add_f32_e32 v0, v0, v14
	v_add_f32_e32 v15, v15, v0
	v_cvt_pk_bf16_f32 v126, v92, v93
	v_cvt_pk_bf16_f32 v127, v94, v95
	v_add_f32_e32 v236, v236, v15
	s_lshl_b32 s55, s47, 14
	v_add_u32_e32 v12, s55, v175
	ds_read_b128 v[128:131], v12
	ds_read_b128 v[132:135], v12 offset:512
	ds_read_b128 v[136:139], v12 offset:2048
	ds_read_b128 v[140:143], v12 offset:2560
	s_lshl_b32 s56, s46, 14
	v_add_u32_e32 v13, s56, v204
	s_add_i32 s6, s45, 3
	s_min_u32 s6, s6, s13
	s_lshl_b32 s6, s6, 13
	s_add_u32 s64, s98, s6
	s_addc_u32 s65, s99, 0
	s_add_i32 s6, s45, 2
	s_min_u32 s6, s6, s13
	s_lshl_b32 s6, s6, 14
	s_add_u32 s6, s100, s6
	s_addc_u32 s7, s101, 0
	s_add_i32 s51, s56, s37
	s_lshl_b32 s57, s54, 14
	s_add_i32 s57, s57, s38
	s_waitcnt vmcnt(0)
	s_and_b64 vcc, exec, s[8:9]
	s_cbranch_vccz .Latt_loop
	s_barrier
